# grid barrier: non-leader workgroups poll the top-level generation word directly (one release hop fewer)
# speedup vs baseline: 1.0095x; 1.0040x over previous
; __device__ __forceinline__ unsigned xb_ld(unsigned* p)              { return __hip_atomic_load(p, __ATOMIC_RELAXED, __HIP_MEMORY_SCOPE_AGENT); }
; __device__ __forceinline__ unsigned xb_add(unsigned* p, unsigned v) { return __hip_atomic_fetch_add(p, v, __ATOMIC_RELAXED, __HIP_MEMORY_SCOPE_AGENT); }
; #define XB_SPIN(cond, bar) do { unsigned _sp = 0; while (cond) { __builtin_amdgcn_s_sleep(1); \
;     if ((++_sp & 255u) == 0u) { if (xb_ld(&(bar)[XB_TMO])) break; if (_sp > XB_SPIN_CAP) { atomicAdd(&(bar)[XB_TMO], 1u); break; } } } } while (0)
; __device__ __forceinline__ void xcd_barrier(const XcdBarrier& b) {
;     ...
;         const unsigned old = xb_add(&bar[XB_XSUB(b.x)], 1u);
;         const unsigned gen = old / nloc;
;         if (old + 1u == (gen + 1u) * nloc) {
;             __builtin_amdgcn_fence(__ATOMIC_RELEASE, "agent");
;             asm volatile("s_waitcnt vmcnt(0)" ::: "memory");
;             const unsigned og = xb_add(&bar[XB_TOP], 1u);
;             const unsigned tg = og / nx;
;             if (og + 1u == (tg + 1u) * nx) xb_add(&bar[XB_TOPGEN], 1u);
;             else XB_SPIN(xb_ld(&bar[XB_TOPGEN]) == tg, bar);
;             __builtin_amdgcn_fence(__ATOMIC_ACQUIRE, "agent");
;             xb_add(&bar[XB_XGEN(b.x)], 1u);
;             asm volatile("s_waitcnt vmcnt(0)" ::: "memory");
;         } else {
;             XB_SPIN(xb_ld(&bar[XB_XGEN(b.x)]) == gen, bar);
;             __builtin_amdgcn_fence(__ATOMIC_ACQUIRE, "agent");
.LBB9_169:
	v_readlane_b32 s4, v254, 45
	v_readlane_b32 s5, v254, 46
	v_cvt_f32_u32_e32 v3, v4
	v_sub_u32_e32 v6, 0, v4
	v_rcp_iflag_f32_e32 v3, v3
	s_nop 1
	global_atomic_add v5, v187, v1, s[4:5] sc0
	v_mul_f32_e32 v3, 0x4f7ffffe, v3
	v_cvt_u32_f32_e32 v3, v3
	v_mul_lo_u32 v6, v6, v3
	v_mul_hi_u32 v6, v3, v6
	v_add_u32_e32 v3, v3, v6
	s_waitcnt vmcnt(0)
	v_mul_hi_u32 v3, v5, v3
	v_mul_lo_u32 v6, v3, v4
	v_sub_u32_e32 v6, v5, v6
	v_add_u32_e32 v7, 1, v3
	v_cmp_ge_u32_e32 vcc, v6, v4
	v_add_u32_e32 v5, 1, v5
	s_nop 0
	v_cndmask_b32_e32 v3, v3, v7, vcc
	v_sub_u32_e32 v7, v6, v4
	v_cndmask_b32_e32 v6, v6, v7, vcc
	v_add_u32_e32 v7, 1, v3
	v_cmp_ge_u32_e32 vcc, v6, v4
	s_nop 1
	v_cndmask_b32_e32 v3, v3, v7, vcc
	v_mul_lo_u32 v6, v4, v3
	v_add_u32_e32 v4, v6, v4
	v_cmp_ne_u32_e32 vcc, v5, v4
	s_and_saveexec_b64 s[4:5], vcc
	s_xor_b64 s[10:11], exec, s[4:5]
	s_cbranch_execz .LBB9_183
	v_readlane_b32 s4, v254, 51
	v_readlane_b32 s5, v254, 52
	s_waitcnt lgkmcnt(0)
	s_nop 3
	global_load_dword v2, v187, s[4:5] sc1
	s_waitcnt vmcnt(0)
	v_cmp_eq_u32_e32 vcc, v2, v3
	s_and_saveexec_b64 s[14:15], vcc
	s_cbranch_execz .LBB9_182
	s_mov_b32 s4, 1
	s_mov_b64 s[18:19], 0
	s_branch .LBB9_173

; __device__ __forceinline__ unsigned xb_ld(unsigned* p)              { return __hip_atomic_load(p, __ATOMIC_RELAXED, __HIP_MEMORY_SCOPE_AGENT); }
; #define XB_SPIN(cond, bar) do { unsigned _sp = 0; while (cond) { __builtin_amdgcn_s_sleep(1); \
;     if ((++_sp & 255u) == 0u) { if (xb_ld(&(bar)[XB_TMO])) break; if (_sp > XB_SPIN_CAP) { atomicAdd(&(bar)[XB_TMO], 1u); break; } } } } while (0)
; __device__ __forceinline__ void xcd_barrier(const XcdBarrier& b) {
;     ...
;             XB_SPIN(xb_ld(&bar[XB_XGEN(b.x)]) == gen, bar);
.LBB9_175:
	v_readlane_b32 s22, v254, 51
	v_readlane_b32 s23, v254, 52
	s_add_i32 s4, s4, 1
	s_mov_b64 s[24:25], -1
	s_nop 2
	global_load_dword v2, v187, s[22:23] sc1
	s_waitcnt vmcnt(0)
	v_cmp_ne_u32_e32 vcc, v2, v3
	s_orn2_b64 s[22:23], vcc, exec
	s_branch .LBB9_172

; __device__ __forceinline__ unsigned xb_ld(unsigned* p)              { return __hip_atomic_load(p, __ATOMIC_RELAXED, __HIP_MEMORY_SCOPE_AGENT); }
; __device__ __forceinline__ unsigned xb_add(unsigned* p, unsigned v) { return __hip_atomic_fetch_add(p, v, __ATOMIC_RELAXED, __HIP_MEMORY_SCOPE_AGENT); }
; #define XB_SPIN(cond, bar) do { unsigned _sp = 0; while (cond) { __builtin_amdgcn_s_sleep(1); \
;     if ((++_sp & 255u) == 0u) { if (xb_ld(&(bar)[XB_TMO])) break; if (_sp > XB_SPIN_CAP) { atomicAdd(&(bar)[XB_TMO], 1u); break; } } } } while (0)
; __device__ __forceinline__ void xcd_barrier(const XcdBarrier& b) {
;     ...
;         const unsigned old = xb_add(&bar[XB_XSUB(b.x)], 1u);
;         const unsigned gen = old / nloc;
;         if (old + 1u == (gen + 1u) * nloc) {
;             __builtin_amdgcn_fence(__ATOMIC_RELEASE, "agent");
;             asm volatile("s_waitcnt vmcnt(0)" ::: "memory");
;             const unsigned og = xb_add(&bar[XB_TOP], 1u);
;             const unsigned tg = og / nx;
;             if (og + 1u == (tg + 1u) * nx) xb_add(&bar[XB_TOPGEN], 1u);
;             else XB_SPIN(xb_ld(&bar[XB_TOPGEN]) == tg, bar);
;             __builtin_amdgcn_fence(__ATOMIC_ACQUIRE, "agent");
;             xb_add(&bar[XB_XGEN(b.x)], 1u);
;             asm volatile("s_waitcnt vmcnt(0)" ::: "memory");
;         } else {
;             XB_SPIN(xb_ld(&bar[XB_XGEN(b.x)]) == gen, bar);
;             __builtin_amdgcn_fence(__ATOMIC_ACQUIRE, "agent");
.LBB9_1689:
	v_readlane_b32 s4, v254, 45
	v_readlane_b32 s5, v254, 46
	v_cvt_f32_u32_e32 v3, v4
	v_sub_u32_e32 v6, 0, v4
	v_rcp_iflag_f32_e32 v3, v3
	s_nop 1
	global_atomic_add v5, v187, v1, s[4:5] sc0
	v_mul_f32_e32 v3, 0x4f7ffffe, v3
	v_cvt_u32_f32_e32 v3, v3
	v_mul_lo_u32 v6, v6, v3
	v_mul_hi_u32 v6, v3, v6
	v_add_u32_e32 v3, v3, v6
	s_waitcnt vmcnt(0)
	v_mul_hi_u32 v3, v5, v3
	v_mul_lo_u32 v6, v3, v4
	v_sub_u32_e32 v6, v5, v6
	v_add_u32_e32 v7, 1, v3
	v_cmp_ge_u32_e32 vcc, v6, v4
	v_add_u32_e32 v5, 1, v5
	s_nop 0
	v_cndmask_b32_e32 v3, v3, v7, vcc
	v_sub_u32_e32 v7, v6, v4
	v_cndmask_b32_e32 v6, v6, v7, vcc
	v_add_u32_e32 v7, 1, v3
	v_cmp_ge_u32_e32 vcc, v6, v4
	s_nop 1
	v_cndmask_b32_e32 v3, v3, v7, vcc
	v_mul_lo_u32 v6, v4, v3
	v_add_u32_e32 v4, v6, v4
	v_cmp_ne_u32_e32 vcc, v5, v4
	s_and_saveexec_b64 s[4:5], vcc
	s_xor_b64 s[14:15], exec, s[4:5]
	s_cbranch_execz .LBB9_1703
	v_readlane_b32 s4, v254, 51
	v_readlane_b32 s5, v254, 52
	s_waitcnt lgkmcnt(0)
	s_nop 3
	global_load_dword v2, v187, s[4:5] sc1
	s_waitcnt vmcnt(0)
	v_cmp_eq_u32_e32 vcc, v2, v3
	s_and_saveexec_b64 s[18:19], vcc
	s_cbranch_execz .LBB9_1702
	s_mov_b32 s4, 1
	s_mov_b64 s[20:21], 0
	s_branch .LBB9_1693

; __device__ __forceinline__ unsigned xb_ld(unsigned* p)              { return __hip_atomic_load(p, __ATOMIC_RELAXED, __HIP_MEMORY_SCOPE_AGENT); }
; #define XB_SPIN(cond, bar) do { unsigned _sp = 0; while (cond) { __builtin_amdgcn_s_sleep(1); \
;     if ((++_sp & 255u) == 0u) { if (xb_ld(&(bar)[XB_TMO])) break; if (_sp > XB_SPIN_CAP) { atomicAdd(&(bar)[XB_TMO], 1u); break; } } } } while (0)
; __device__ __forceinline__ void xcd_barrier(const XcdBarrier& b) {
;     ...
;             XB_SPIN(xb_ld(&bar[XB_XGEN(b.x)]) == gen, bar);
.LBB9_1695:
	v_readlane_b32 s24, v254, 51
	v_readlane_b32 s25, v254, 52
	s_add_i32 s4, s4, 1
	s_mov_b64 s[26:27], -1
	s_nop 2
	global_load_dword v2, v187, s[24:25] sc1
	s_waitcnt vmcnt(0)
	v_cmp_ne_u32_e32 vcc, v2, v3
	s_orn2_b64 s[24:25], vcc, exec
	s_branch .LBB9_1692
